# T10: dil KV loop stores V row-major with one ds_write_b128 (pitch 192) and reads PV A-operand with ds_read_b64_tr_b16 instead of 8 ds_write_b16 + ds_read2_b64
# speedup vs baseline: 1.0489x; 1.0031x over previous
; __device__ __forceinline__ float sum32(float v) { auto rr = __builtin_amdgcn_permlane32_swap(__float_as_uint(v), __float_as_uint(v), false, false); return __uint_as_float(rr[0]) + __uint_as_float(rr[1]); }
; __device__ __forceinline__ unsigned cvtpk(float lo, float hi) { f32x2_t v = {lo, hi}; bf16x2_t b = __builtin_convertvector(v, bf16x2_t); return __builtin_bit_cast(unsigned, b); }
; template <bool NORM> __device__ __forceinline__ void load_qfrag(bf16x8 (&qf)[4], const bf16_t* qrow, const float* g1, const float* g2, float sc, int hh) {
;     ...
;         ss = sum32(ss); sc *= rsqrtf(ss * (1.f / 64.f) + EPS); }
; #pragma unroll
;     for (int s = 0; s < 4; ++s) { float v[8];
; #pragma unroll
;         for (int j = 0; j < 8; ++j) { const int d = 16 * s + 8 * hh + j; v[j] = f[8 * s + j] * sc * (g1 ? g1[d] : 1.f) * (g2 ? g2[d] : 1.f); }
;         u32x4 w; w.x = cvtpk(v[0], v[1]); w.y = cvtpk(v[2], v[3]); w.z = cvtpk(v[4], v[5]); w.w = cvtpk(v[6], v[7]);
;         qf[s] = __builtin_bit_cast(bf16x8, w); }
; __device__ __forceinline__ void dil_item(const DilArgs& A, int item, LAS unsigned char* lds, int tid) {
;     ...
;     const int dil = cfg == 0 ? 1 : (cfg == 1 ? 4 : 16), nq = 16 / dil, c = sub / nq, qt = sub % nq, i0 = 256 * qt, L = SEQ / dil;
;     const int lane = tid & 63, w = __builtin_amdgcn_readfirstlane(tid >> 6), r = lane & 31, hh = lane >> 5;
;     const int iq = i0 + 32 * w + r, tq = c + dil * iq; const size_t token = (size_t)b * SEQ + tq;
;     const bf16_t* base = A.proj + (size_t)b * SEQ * NP;
;     const float slope = exp2f(-(float)(2 * head + 2)) * (float)dil * LOG2E;
;     bf16x8 qf[4]; load_qfrag<true>(qf, base + (size_t)tq * NP + C_QD + head * 64, A.g_q, nullptr, 0.125f * LOG2E, hh);
;     const bf16_t* kp = base + (size_t)c * NP + C_KD + head * 64; const bf16_t* vp = base + (size_t)c * NP + C_VD + head * 64;
;     const int kb_lo = (i0 >> 6) >= 2 ? (i0 >> 6) - 2 : 0, kb_hi = (i0 >> 6) + 3, q_lo = i0 + 32 * w;
;     f32x16 o0, o1;
; #pragma unroll
;     for (int i = 0; i < 16; ++i) { o0[i] = 0.f; o1[i] = 0.f; }
;     float m = -INFINITY, l = 0.f, dummy = 0.f;
.LBB0_862:
	s_or_b64 exec, exec, s[4:5]
	v_rsq_f32_e32 v80, v80
	s_or_b32 s24, s36, 3
	v_mul_u32_u24_e32 v111, 0x90, v21
	v_bfe_u32 v109, v21, 2, 2
	v_lshl_add_u32 v109, v106, 2, v109
	v_mul_u32_u24_e32 v112, 0xc0, v109
	v_bfe_u32 v109, v21, 4, 1
	v_lshl_add_u32 v112, v109, 5, v112
	v_and_b32_e32 v109, 3, v21
	v_lshl_add_u32 v112, v109, 3, v112
	v_mul_f32_e32 v81, 0x45800000, v80
	v_cndmask_b32_e64 v80, v80, v81, s[0:1]
	v_mul_f32_e32 v88, 0x3e38aa3b, v80
	v_pk_mul_f32 v[16:17], v[88:89], v[16:17] op_sel_hi:[0,1]
	s_waitcnt vmcnt(0)
	v_pk_mul_f32 v[16:17], v[16:17], v[22:23]
	v_pk_mul_f32 v[10:11], v[88:89], v[10:11] op_sel_hi:[0,1]
	v_pk_mul_f32 v[22:23], v[10:11], v[26:27]
	v_cvt_pk_bf16_f32 v10, v16, v17
	v_mul_f32_e32 v16, v88, v54
	v_mul_f32_e32 v17, v88, v53
	v_mul_f32_e32 v16, v16, v78
	v_mul_f32_e32 v17, v17, v77
	v_cvt_pk_bf16_f32 v83, v16, v17
	v_mul_f32_e32 v16, v88, v46
	v_mul_f32_e32 v17, v88, v45
	s_and_b64 s[0:1], s[6:7], exec
	v_mul_f32_e32 v16, v16, v70
	v_mul_f32_e32 v17, v17, v69
	s_cselect_b32 s4, 4, 16
	s_and_b64 s[0:1], s[8:9], exec
	v_cvt_pk_bf16_f32 v87, v16, v17
	v_mul_f32_e32 v16, v88, v38
	v_mul_f32_e32 v17, v88, v37
	s_cselect_b32 s4, 1, s4
	s_lshl_b32 s0, s15, 1
	v_mul_f32_e32 v16, v16, v62
	v_mul_f32_e32 v17, v17, v61
	s_add_i32 s0, s0, 2
	v_cvt_pk_bf16_f32 v91, v16, v17
	v_cvt_f32_ubyte0_e32 v16, s0
	s_mov_b32 s0, 0x42fc0000
	v_cmp_lt_f32_e32 vcc, s0, v16
	s_and_b64 s[0:1], vcc, exec
	v_pk_mul_f32 v[18:19], v[88:89], v[18:19] op_sel_hi:[0,1]
	v_cndmask_b32_e32 v17, 0, v214, vcc
	v_sub_f32_e32 v16, v17, v16
	v_exp_f32_e32 v16, v16
	v_pk_mul_f32 v[12:13], v[88:89], v[12:13] op_sel_hi:[0,1]
	s_cselect_b32 s0, 0xffffffc0, 0
	v_pk_mul_f32 v[12:13], v[12:13], v[24:25]
	v_pk_mul_f32 v[18:19], v[18:19], v[28:29]
	v_ldexp_f32 v16, v16, s0
	v_cvt_f32_ubyte0_e32 v17, s4
	v_cvt_pk_bf16_f32 v11, v12, v13
	v_cvt_pk_bf16_f32 v12, v22, v23
	v_cvt_pk_bf16_f32 v13, v18, v19
	v_mul_f32_e32 v18, v88, v52
	v_mul_f32_e32 v19, v88, v51
	v_mul_f32_e32 v22, v88, v50
	v_mul_f32_e32 v23, v88, v49
	v_mul_f32_e32 v24, v88, v48
	v_mul_f32_e32 v25, v88, v47
	v_mul_f32_e32 v16, v16, v17
	v_mul_f32_e32 v18, v18, v76
	v_mul_f32_e32 v19, v19, v75
	v_mul_f32_e32 v22, v22, v74
	v_mul_f32_e32 v23, v23, v73
	v_mul_f32_e32 v24, v24, v72
	v_mul_f32_e32 v25, v25, v71
	v_mul_f32_e32 v93, 0x3fb8aa3b, v16
	v_and_b32_e32 v16, 7, v30
	v_cvt_pk_bf16_f32 v80, v24, v25
	v_cvt_pk_bf16_f32 v81, v22, v23
	v_cvt_pk_bf16_f32 v82, v18, v19
	v_mul_f32_e32 v18, v88, v44
	v_mul_f32_e32 v19, v88, v43
	v_mul_f32_e32 v22, v88, v42
	v_mul_f32_e32 v23, v88, v41
	v_mul_f32_e32 v24, v88, v40
	v_mul_f32_e32 v25, v88, v39
	v_lshlrev_b32_e32 v108, 4, v16
	s_nop 0
	v_lshlrev_b32_e32 v16, 1, v20
	v_mov_b32_e32 v17, v1
	v_mul_f32_e32 v18, v18, v68
	v_mul_f32_e32 v19, v19, v67
	v_mul_f32_e32 v22, v22, v66
	v_mul_f32_e32 v23, v23, v65
	v_mul_f32_e32 v24, v24, v64
	v_mul_f32_e32 v25, v25, v63
	v_lshl_add_u64 v[102:103], s[16:17], 0, v[16:17]
	v_lshl_add_u64 v[104:105], s[26:27], 0, v[16:17]
	v_mul_i32_i24_e32 v16, -4, v106
	v_cvt_pk_bf16_f32 v84, v24, v25
	v_cvt_pk_bf16_f32 v85, v22, v23
	v_cvt_pk_bf16_f32 v86, v18, v19
	v_mul_f32_e32 v18, v88, v36
	v_mul_f32_e32 v19, v88, v35
	v_mul_f32_e32 v22, v88, v34
	v_mul_f32_e32 v23, v88, v33
	v_mul_f32_e32 v24, v88, v32
	v_mul_f32_e32 v25, v88, v31
	v_add3_u32 v16, v16, s42, v21
	v_mul_f32_e32 v18, v18, v60
	v_mul_f32_e32 v19, v19, v59
	v_mul_f32_e32 v22, v22, v58
	v_mul_f32_e32 v23, v23, v57
	v_mul_f32_e32 v24, v24, v56
	v_mul_f32_e32 v25, v25, v55
	v_subrev_u32_e32 v16, s43, v16
	v_mov_b32_e32 v30, v1
	v_mov_b32_e32 v31, v1
	v_cvt_pk_bf16_f32 v88, v24, v25
	v_cvt_pk_bf16_f32 v89, v22, v23
	v_cvt_pk_bf16_f32 v90, v18, v19
	s_movk_i32 s0, 0x90
	v_subrev_u32_e32 v113, 27, v16
	v_mov_b32_e32 v16, v1
	v_mov_b32_e32 v18, v1
	v_mov_b32_e32 v19, v1
	v_mov_b32_e32 v20, v1
	v_mov_b32_e32 v21, v1
	v_mov_b32_e32 v22, v1
	v_mov_b32_e32 v23, v1
	v_mov_b32_e32 v24, v1
	v_mov_b32_e32 v25, v1
	v_mov_b32_e32 v26, v1
	v_mov_b32_e32 v27, v1
	v_mov_b32_e32 v28, v1
	v_mov_b32_e32 v29, v1
	v_mov_b64_e32 v[46:47], v[30:31]
	s_mov_b32 s6, 0
	v_mul_lo_u32 v95, v79, s0
	v_mul_u32_u24_e32 v110, 0xc0, v79
	v_add_u32_e32 v110, v110, v108
	s_add_i32 s7, s42, 0xffffff80
	s_or_b32 s8, s42, 31
	v_add_u32_e32 v114, 64, v79
	v_mov_b32_e32 v115, 0xff800000
	v_mov_b64_e32 v[44:45], v[28:29]
	v_mov_b64_e32 v[42:43], v[26:27]
	v_mov_b64_e32 v[40:41], v[24:25]
	v_mov_b64_e32 v[38:39], v[22:23]
	v_mov_b64_e32 v[36:37], v[20:21]
	v_mov_b64_e32 v[34:35], v[18:19]
	v_mov_b64_e32 v[32:33], v[16:17]
; #define LAS __attribute__((address_space(3)))
; template <int K> __device__ __forceinline__ float swz_f(float v) { return __uint_as_float(swz_u<K>(__float_as_uint(v))); }
; #define UNPACK8(v, k) const float k##0 = blo(v.x), k##1 = bhi(v.x), k##2 = blo(v.y), k##3 = bhi(v.y), k##4 = blo(v.z), k##5 = bhi(v.z), k##6 = blo(v.w), k##7 = bhi(v.w)
; __device__ __forceinline__ unsigned cvtpk(float lo, float hi) { f32x2_t v = {lo, hi}; bf16x2_t b = __builtin_convertvector(v, bf16x2_t); return __builtin_bit_cast(unsigned, b); }
; template <bool NORM> __device__ __forceinline__ void kv_store(u32x4 kc, u32x4 vc, const float (&g)[8], LAS unsigned char* ksb, LAS unsigned char* vtb, int tid) {
;     const int kl = tid >> 3, ch = tid & 7;
;     if (NORM) { UNPACK8(kc, k); float ss = (k0 * k0 + k1 * k1) + (k2 * k2 + k3 * k3) + (k4 * k4 + k5 * k5) + (k6 * k6 + k7 * k7);
;         ss += swz_f<1>(ss); ss += swz_f<2>(ss); ss += swz_f<4>(ss);
;         const float rs = rsqrtf(ss * (1.f / 64.f) + EPS);
;         kc.x = cvtpk(k0 * rs * g[0], k1 * rs * g[1]); kc.y = cvtpk(k2 * rs * g[2], k3 * rs * g[3]); kc.z = cvtpk(k4 * rs * g[4], k5 * rs * g[5]); kc.w = cvtpk(k6 * rs * g[6], k7 * rs * g[7]); }
;     *(LAS u32x4*)(ksb + kl * KSB + ch * 16) = kc;
;     LAS unsigned short* vp = (LAS unsigned short*)(vtb + (8 * ch) * VTB + kl * 2);
;     vp[0 * (VTB / 2)] = (unsigned short)(vc.x & 0xffffu); vp[1 * (VTB / 2)] = (unsigned short)(vc.x >> 16);
;     vp[2 * (VTB / 2)] = (unsigned short)(vc.y & 0xffffu); vp[3 * (VTB / 2)] = (unsigned short)(vc.y >> 16);
;     vp[4 * (VTB / 2)] = (unsigned short)(vc.z & 0xffffu); vp[5 * (VTB / 2)] = (unsigned short)(vc.z >> 16);
;     vp[6 * (VTB / 2)] = (unsigned short)(vc.w & 0xffffu); vp[7 * (VTB / 2)] = (unsigned short)(vc.w >> 16);
; }
.LBB0_863:
	s_waitcnt vmcnt(1)
	v_and_b32_e32 v53, 0xffff0000, v5
	v_and_b32_e32 v51, 0xffff0000, v4
	v_lshlrev_b32_e32 v52, 16, v5
	v_lshlrev_b32_e32 v50, 16, v4
	v_mov_b32_e32 v54, v53
	v_mov_b32_e32 v55, v51
	v_mov_b32_e32 v48, v52
	v_mov_b32_e32 v49, v50
	v_pk_mul_f32 v[54:55], v[54:55], v[54:55]
	v_and_b32_e32 v57, 0xffff0000, v2
	v_pk_fma_f32 v[48:49], v[48:49], v[48:49], v[54:55]
	v_and_b32_e32 v55, 0xffff0000, v3
	v_lshlrev_b32_e32 v54, 16, v3
	v_lshlrev_b32_e32 v56, 16, v2
	v_mov_b32_e32 v60, v57
	v_mov_b32_e32 v61, v55
	v_mov_b32_e32 v58, v56
	v_mov_b32_e32 v59, v54
	v_pk_mul_f32 v[60:61], v[60:61], v[60:61]
	s_mul_i32 s0, s6, 0x2400
	s_mul_i32 s98, s6, 0x3000
	v_pk_fma_f32 v[58:59], v[58:59], v[58:59], v[60:61]
	s_add_i32 s16, s0, 0
	v_add_f32_e32 v58, v58, v59
	v_add_f32_e32 v49, v49, v58
	v_add_f32_e32 v48, v48, v49
	s_lshl_b32 s0, s6, 9
	s_sub_i32 s9, s16, s0
	s_cmp_ge_u32 s13, s24
	s_cselect_b64 s[4:5], -1, 0
	s_nop 1
	v_add_f32_dpp v48, v48, v48 quad_perm:[1,0,3,2] row_mask:0xf bank_mask:0xf
	s_nop 1
	v_add_f32_dpp v48, v48, v48 quad_perm:[2,3,0,1] row_mask:0xf bank_mask:0xf
	s_nop 1
	v_add_f32_dpp v48, v48, v48 row_half_mirror row_mask:0xf bank_mask:0xf
	v_fmamk_f32 v48, v48, 0x3c800000, v139
	v_mul_f32_e32 v49, 0x4b800000, v48
	v_cmp_gt_f32_e32 vcc, s71, v48
	s_nop 1
	v_cndmask_b32_e32 v48, v48, v49, vcc
	v_rsq_f32_e32 v48, v48
	s_nop 0
	v_mul_f32_e32 v49, 0x45800000, v48
	v_cndmask_b32_e32 v58, v48, v49, vcc
	v_pk_mul_f32 v[48:49], v[58:59], v[56:57] op_sel_hi:[0,1]
	v_pk_mul_f32 v[54:55], v[58:59], v[54:55] op_sel_hi:[0,1]
	v_pk_mul_f32 v[50:51], v[58:59], v[50:51] op_sel_hi:[0,1]
	v_pk_mul_f32 v[52:53], v[58:59], v[52:53] op_sel_hi:[0,1]
	v_pk_mul_f32 v[48:49], v[14:15], v[48:49]
	v_pk_mul_f32 v[54:55], v[96:97], v[54:55]
	v_pk_mul_f32 v[50:51], v[98:99], v[50:51]
	v_pk_mul_f32 v[52:53], v[100:101], v[52:53]
	v_cvt_pk_bf16_f32 v48, v48, v49
	v_cvt_pk_bf16_f32 v49, v54, v55
	v_cvt_pk_bf16_f32 v50, v50, v51
	v_cvt_pk_bf16_f32 v51, v52, v53
	v_add3_u32 v52, s16, v95, v108
	ds_write_b128 v52, v[48:51]
	v_add_u32_e32 v48, s98, v110
	s_and_b64 vcc, exec, s[4:5]
	s_waitcnt vmcnt(0)
	ds_write_b128 v48, v[6:9] offset:18432
	s_waitcnt lgkmcnt(0)
	s_barrier
	s_cbranch_vccnz .LBB0_867
	v_add_u32_e32 v48, s43, v114
	v_cmp_lt_i32_e32 vcc, -1, v48
	v_cmp_gt_i32_e64 s[0:1], s30, v48
	s_and_b64 s[26:27], vcc, s[0:1]
	v_mov_b32_e32 v9, 0
	v_mov_b32_e32 v5, 0
	v_mov_b32_e32 v4, 0
	v_mov_b32_e32 v3, 0
	v_mov_b32_e32 v2, 0
	v_mov_b32_e32 v8, 0
	v_mov_b32_e32 v7, 0
	v_mov_b32_e32 v6, 0
	s_and_saveexec_b64 s[0:1], s[26:27]
	s_cbranch_execz .LBB0_866
	v_mad_u64_u32 v[2:3], s[26:27], s44, v48, 0
	v_lshlrev_b64 v[2:3], 1, v[2:3]
	v_lshl_add_u64 v[4:5], v[102:103], 0, v[2:3]
	v_lshl_add_u64 v[6:7], v[104:105], 0, v[2:3]
	global_load_dwordx4 v[2:5], v[4:5], off
	s_nop 0
	global_load_dwordx4 v[6:9], v[6:7], off

; #define LAS __attribute__((address_space(3)))
; __device__ __forceinline__ unsigned cvtpk(float lo, float hi) { f32x2_t v = {lo, hi}; bf16x2_t b = __builtin_convertvector(v, bf16x2_t); return __builtin_bit_cast(unsigned, b); }
; #define MFMA32(a, b, c) __builtin_amdgcn_mfma_f32_32x32x16_bf16((a), (b), (c), 0, 0, 0)
; __device__ __forceinline__ void pv_accum(const f32x16& s0, const f32x16& s1, f32x16& o0, f32x16& o1, LAS const unsigned char* vtb, int r, int hh) {
;     __builtin_amdgcn_s_setprio(1);
; #pragma unroll
;     for (int kt = 0; kt < 2; ++kt)
; #pragma unroll
;         for (int sp = 0; sp < 2; ++sp) { u32x4 w;
;             if (kt == 0) { w.x = cvtpk(s0[8 * sp], s0[8 * sp + 1]); w.y = cvtpk(s0[8 * sp + 2], s0[8 * sp + 3]); w.z = cvtpk(s0[8 * sp + 4], s0[8 * sp + 5]); w.w = cvtpk(s0[8 * sp + 6], s0[8 * sp + 7]); }
;             else         { w.x = cvtpk(s1[8 * sp], s1[8 * sp + 1]); w.y = cvtpk(s1[8 * sp + 2], s1[8 * sp + 3]); w.z = cvtpk(s1[8 * sp + 4], s1[8 * sp + 5]); w.w = cvtpk(s1[8 * sp + 6], s1[8 * sp + 7]); }
;             const bf16x8 pb = __builtin_bit_cast(bf16x8, w); const int ko = 32 * kt + 16 * sp + 4 * hh;
;             { const s16x4 lo = *(LAS const s16x4*)(vtb + r * VTB + ko * 2), hi = *(LAS const s16x4*)(vtb + r * VTB + (ko + 8) * 2);
;               o0 = MFMA32(__builtin_shufflevector(lo, hi, 0, 1, 2, 3, 4, 5, 6, 7), pb, o0); }
;             { const s16x4 lo = *(LAS const s16x4*)(vtb + (32 + r) * VTB + ko * 2), hi = *(LAS const s16x4*)(vtb + (32 + r) * VTB + (ko + 8) * 2);
;               o1 = MFMA32(__builtin_shufflevector(lo, hi, 0, 1, 2, 3, 4, 5, 6, 7), pb, o1); } }
;     __builtin_amdgcn_s_setprio(0);
.LBB0_870:
	v_add_f32_e32 v117, v117, v118
	v_fmac_f32_e32 v117, v107, v48
	s_setprio 1
	v_add_u32_e32 v48, s98, v112
	s_nop 0
	ds_read_b64_tr_b16 v[118:119], v48 offset:18432
	ds_read_b64_tr_b16 v[120:121], v48 offset:19968
	v_cvt_pk_bf16_f32 v190, v62, v64
	v_cvt_pk_bf16_f32 v191, v66, v68
	v_cvt_pk_bf16_f32 v192, v70, v72
	v_cvt_pk_bf16_f32 v193, v74, v76
	s_nop 0
	v_cvt_pk_bf16_f32 v70, v71, v73
	v_cvt_pk_bf16_f32 v71, v75, v77
	ds_read_b64_tr_b16 v[74:75], v48 offset:21568
	ds_read_b64_tr_b16 v[76:77], v48 offset:23104
	s_waitcnt lgkmcnt(2)
	v_mfma_f32_32x32x16_bf16 v[16:31], v[118:121], v[190:193], v[16:31]
	ds_read_b64_tr_b16 v[118:119], v48 offset:18496
	ds_read_b64_tr_b16 v[120:121], v48 offset:20032
	v_cvt_pk_bf16_f32 v72, v78, v79
	v_cvt_pk_bf16_f32 v73, v115, v116
	v_cvt_pk_bf16_f32 v50, v50, v51
	v_cvt_pk_bf16_f32 v51, v52, v53
	v_cvt_pk_bf16_f32 v52, v54, v56
	v_cvt_pk_bf16_f32 v53, v58, v60
	v_cvt_pk_bf16_f32 v54, v55, v57
	s_waitcnt lgkmcnt(0)
	v_mfma_f32_32x32x16_bf16 v[32:47], v[118:121], v[190:193], v[32:47]
	ds_read_b64_tr_b16 v[118:119], v48 offset:21504
	ds_read_b64_tr_b16 v[120:121], v48 offset:23040
	v_cvt_pk_bf16_f32 v55, v59, v61
	v_cvt_pk_bf16_f32 v56, v63, v65
	v_cvt_pk_bf16_f32 v57, v67, v69
	s_waitcnt lgkmcnt(0)
	v_mfma_f32_32x32x16_bf16 v[16:31], v[118:121], v[70:73], v[16:31]
	v_mfma_f32_32x32x16_bf16 v[32:47], v[74:77], v[70:73], v[32:47]
	ds_read_b64_tr_b16 v[70:71], v48 offset:24576
	ds_read_b64_tr_b16 v[72:73], v48 offset:26112
	s_waitcnt lgkmcnt(0)
	v_mfma_f32_32x32x16_bf16 v[16:31], v[70:73], v[50:53], v[16:31]
	ds_read_b64_tr_b16 v[70:71], v48 offset:24640
	ds_read_b64_tr_b16 v[72:73], v48 offset:26176
	s_waitcnt lgkmcnt(0)
	v_mfma_f32_32x32x16_bf16 v[32:47], v[70:73], v[50:53], v[32:47]
	ds_read_b64_tr_b16 v[50:51], v48 offset:27648
	ds_read_b64_tr_b16 v[52:53], v48 offset:29184
	s_waitcnt lgkmcnt(0)
	v_mfma_f32_32x32x16_bf16 v[16:31], v[50:53], v[54:57], v[16:31]
	ds_read_b64_tr_b16 v[50:51], v48 offset:27712
	ds_read_b64_tr_b16 v[52:53], v48 offset:29248
	s_waitcnt lgkmcnt(0)
	v_mfma_f32_32x32x16_bf16 v[32:47], v[50:53], v[54:57], v[32:47]
	s_setprio 0
	v_mov_b32_e32 v107, v117
	s_branch .LBB0_872
